# attention: V tile DMA issued before the K tile DMA in the vector segment
# baseline (speedup 1.0000x reference)
.Lattn_tb4:
	ds_read_b128 v[216:219], v187 offset:16384
	ds_read_b128 v[220:223], v187 offset:20480
	ds_read_b128 v[224:227], v187 offset:24576
	ds_read_b128 v[228:231], v187 offset:28672
	ds_read_b128 v[208:211], v188 offset:16384
	ds_read_b128 v[212:215], v188 offset:20480
	v_exp_f32_e32 v171, v96
	v_exp_f32_e32 v173, v97
	v_exp_f32_e32 v179, v98
	s_add_i32 m0, s5, 114688
	v_exp_f32_e32 v180, v99
	v_exp_f32_e32 v232, v100
	v_exp_f32_e32 v233, v101
	global_load_lds_dwordx4 v172, s[52:53]
	v_exp_f32_e32 v234, v102
	v_exp_f32_e32 v235, v103
	v_add_f32_e32 v190, v171, v173
	s_add_i32 m0, s5, 122880
	v_add_f32_e32 v191, v179, v180
	v_add_f32_e32 v190, v190, v232
	v_add_f32_e32 v191, v191, v233
	global_load_lds_dwordx4 v172, s[54:55]
	v_add_f32_e32 v190, v190, v234
	v_add_f32_e32 v191, v191, v235
	v_cvt_pk_bf16_f32 v144, v171, v173
	s_add_i32 m0, s5, 16384
	v_cvt_pk_bf16_f32 v145, v179, v180
	v_cvt_pk_bf16_f32 v146, v232, v233
	v_cvt_pk_bf16_f32 v147, v234, v235
	global_load_lds_dwordx4 v170, s[48:49]
	v_exp_f32_e32 v171, v104
	v_exp_f32_e32 v173, v105
	v_exp_f32_e32 v179, v106
	s_add_i32 m0, s5, 24576
	v_exp_f32_e32 v180, v107
	v_exp_f32_e32 v232, v108
	v_exp_f32_e32 v233, v109
	global_load_lds_dwordx4 v170, s[50:51]
	v_exp_f32_e32 v234, v110
	v_exp_f32_e32 v235, v111
	v_add_f32_e32 v190, v190, v171
	v_add_f32_e32 v191, v191, v173
	v_add_f32_e32 v190, v190, v179
	v_add_f32_e32 v191, v191, v180
	v_add_f32_e32 v190, v190, v232
	v_add_f32_e32 v191, v191, v233
	v_add_f32_e32 v190, v190, v234
	v_add_f32_e32 v191, v191, v235
	v_cvt_pk_bf16_f32 v148, v171, v173
	v_cvt_pk_bf16_f32 v149, v179, v180
	v_cvt_pk_bf16_f32 v150, v232, v233
	v_cvt_pk_bf16_f32 v151, v234, v235
	v_exp_f32_e32 v171, v112
	v_exp_f32_e32 v173, v113
	v_exp_f32_e32 v179, v114
	v_exp_f32_e32 v180, v115
	v_exp_f32_e32 v232, v116
	v_exp_f32_e32 v233, v117
	v_exp_f32_e32 v234, v118
	v_exp_f32_e32 v235, v119
	v_add_f32_e32 v190, v190, v171
	v_add_f32_e32 v191, v191, v173
	v_add_f32_e32 v190, v190, v179
	v_add_f32_e32 v191, v191, v180
	v_add_f32_e32 v190, v190, v232
	v_add_f32_e32 v191, v191, v233
	v_add_f32_e32 v190, v190, v234
	v_add_f32_e32 v191, v191, v235
	v_cvt_pk_bf16_f32 v152, v171, v173
	v_cvt_pk_bf16_f32 v153, v179, v180
	v_cvt_pk_bf16_f32 v154, v232, v233
	v_cvt_pk_bf16_f32 v155, v234, v235
	v_exp_f32_e32 v171, v120
	v_exp_f32_e32 v173, v121
	v_exp_f32_e32 v179, v122
	v_exp_f32_e32 v180, v123
	v_exp_f32_e32 v232, v124
	v_exp_f32_e32 v233, v125
	v_exp_f32_e32 v234, v126
	v_exp_f32_e32 v235, v127
	v_add_f32_e32 v190, v190, v171
	v_add_f32_e32 v191, v191, v173
	v_add_f32_e32 v190, v190, v179
	v_add_f32_e32 v191, v191, v180
	v_add_f32_e32 v190, v190, v232
	v_add_f32_e32 v191, v191, v233
	v_add_f32_e32 v190, v190, v234
	v_add_f32_e32 v191, v191, v235
	v_add_f32_e32 v190, v190, v191
	v_cmp_ngt_f32_e32 vcc, 0x71800000, v190
	v_cvt_pk_bf16_f32 v156, v171, v173
	v_cvt_pk_bf16_f32 v157, v179, v180
	v_cvt_pk_bf16_f32 v158, v232, v233
	v_cvt_pk_bf16_f32 v159, v234, v235
	s_nop 0
	s_cbranch_vccnz .Lattn_redo_L0
	v_add_f32_e32 v167, v167, v190
	s_cmp_lg_u32 s14, 0
	s_cbranch_scc1 .Lattn_tb5
	s_waitcnt vmcnt(4)
	s_barrier

.Lattn_tb6:
	ds_read_b128 v[216:219], v187 offset:32768
	ds_read_b128 v[220:223], v187 offset:36864
	ds_read_b128 v[224:227], v187 offset:40960
	ds_read_b128 v[228:231], v187 offset:45056
	ds_read_b128 v[208:211], v188 offset:32768
	ds_read_b128 v[212:215], v188 offset:36864
	v_exp_f32_e32 v171, v64
	v_exp_f32_e32 v173, v65
	v_exp_f32_e32 v179, v66
	s_add_i32 m0, s5, 65536
	v_exp_f32_e32 v180, v67
	v_exp_f32_e32 v232, v68
	v_exp_f32_e32 v233, v69
	global_load_lds_dwordx4 v172, s[52:53]
	v_exp_f32_e32 v234, v70
	v_exp_f32_e32 v235, v71
	v_add_f32_e32 v190, v171, v173
	s_add_i32 m0, s5, 73728
	v_add_f32_e32 v191, v179, v180
	v_add_f32_e32 v190, v190, v232
	v_add_f32_e32 v191, v191, v233
	global_load_lds_dwordx4 v172, s[54:55]
	v_add_f32_e32 v190, v190, v234
	v_add_f32_e32 v191, v191, v235
	v_cvt_pk_bf16_f32 v144, v171, v173
	s_add_i32 m0, s5, 32768
	v_cvt_pk_bf16_f32 v145, v179, v180
	v_cvt_pk_bf16_f32 v146, v232, v233
	v_cvt_pk_bf16_f32 v147, v234, v235
	global_load_lds_dwordx4 v170, s[48:49]
	v_exp_f32_e32 v171, v72
	v_exp_f32_e32 v173, v73
	v_exp_f32_e32 v179, v74
	s_add_i32 m0, s5, 40960
	v_exp_f32_e32 v180, v75
	v_exp_f32_e32 v232, v76
	v_exp_f32_e32 v233, v77
	global_load_lds_dwordx4 v170, s[50:51]
	v_exp_f32_e32 v234, v78
	v_exp_f32_e32 v235, v79
	v_add_f32_e32 v190, v190, v171
	v_add_f32_e32 v191, v191, v173
	v_add_f32_e32 v190, v190, v179
	v_add_f32_e32 v191, v191, v180
	v_add_f32_e32 v190, v190, v232
	v_add_f32_e32 v191, v191, v233
	v_add_f32_e32 v190, v190, v234
	v_add_f32_e32 v191, v191, v235
	v_cvt_pk_bf16_f32 v148, v171, v173
	v_cvt_pk_bf16_f32 v149, v179, v180
	v_cvt_pk_bf16_f32 v150, v232, v233
	v_cvt_pk_bf16_f32 v151, v234, v235
	v_exp_f32_e32 v171, v80
	v_exp_f32_e32 v173, v81
	v_exp_f32_e32 v179, v82
	v_exp_f32_e32 v180, v83
	v_exp_f32_e32 v232, v84
	v_exp_f32_e32 v233, v85
	v_exp_f32_e32 v234, v86
	v_exp_f32_e32 v235, v87
	v_add_f32_e32 v190, v190, v171
	v_add_f32_e32 v191, v191, v173
	v_add_f32_e32 v190, v190, v179
	v_add_f32_e32 v191, v191, v180
	v_add_f32_e32 v190, v190, v232
	v_add_f32_e32 v191, v191, v233
	v_add_f32_e32 v190, v190, v234
	v_add_f32_e32 v191, v191, v235
	v_cvt_pk_bf16_f32 v152, v171, v173
	v_cvt_pk_bf16_f32 v153, v179, v180
	v_cvt_pk_bf16_f32 v154, v232, v233
	v_cvt_pk_bf16_f32 v155, v234, v235
	v_exp_f32_e32 v171, v88
	v_exp_f32_e32 v173, v89
	v_exp_f32_e32 v179, v90
	v_exp_f32_e32 v180, v91
	v_exp_f32_e32 v232, v92
	v_exp_f32_e32 v233, v93
	v_exp_f32_e32 v234, v94
	v_exp_f32_e32 v235, v95
	v_add_f32_e32 v190, v190, v171
	v_add_f32_e32 v191, v191, v173
	v_add_f32_e32 v190, v190, v179
	v_add_f32_e32 v191, v191, v180
	v_add_f32_e32 v190, v190, v232
	v_add_f32_e32 v191, v191, v233
	v_add_f32_e32 v190, v190, v234
	v_add_f32_e32 v191, v191, v235
	v_add_f32_e32 v190, v190, v191
	v_cmp_ngt_f32_e32 vcc, 0x71800000, v190
	v_cvt_pk_bf16_f32 v156, v171, v173
	v_cvt_pk_bf16_f32 v157, v179, v180
	v_cvt_pk_bf16_f32 v158, v232, v233
	v_cvt_pk_bf16_f32 v159, v234, v235
	s_nop 0
	s_cbranch_vccnz .Lattn_redo_L1
	v_add_f32_e32 v167, v167, v190
	s_cmp_lg_u32 s14, 0
	s_cbranch_scc1 .Lattn_tb7
	s_waitcnt vmcnt(4)
	s_barrier

.Lattn_tb8:
	ds_read_b128 v[216:219], v187 offset:49152
	ds_read_b128 v[220:223], v187 offset:53248
	ds_read_b128 v[224:227], v187 offset:57344
	ds_read_b128 v[228:231], v187 offset:61440
	ds_read_b128 v[208:211], v188 offset:49152
	ds_read_b128 v[212:215], v188 offset:53248
	v_exp_f32_e32 v171, v96
	v_exp_f32_e32 v173, v97
	v_exp_f32_e32 v179, v98
	s_add_i32 m0, s5, 81920
	v_exp_f32_e32 v180, v99
	v_exp_f32_e32 v232, v100
	v_exp_f32_e32 v233, v101
	global_load_lds_dwordx4 v172, s[52:53]
	v_exp_f32_e32 v234, v102
	v_exp_f32_e32 v235, v103
	v_add_f32_e32 v190, v171, v173
	s_add_i32 m0, s5, 90112
	v_add_f32_e32 v191, v179, v180
	v_add_f32_e32 v190, v190, v232
	v_add_f32_e32 v191, v191, v233
	global_load_lds_dwordx4 v172, s[54:55]
	v_add_f32_e32 v190, v190, v234
	v_add_f32_e32 v191, v191, v235
	v_cvt_pk_bf16_f32 v144, v171, v173
	s_add_i32 m0, s5, 49152
	v_cvt_pk_bf16_f32 v145, v179, v180
	v_cvt_pk_bf16_f32 v146, v232, v233
	v_cvt_pk_bf16_f32 v147, v234, v235
	global_load_lds_dwordx4 v170, s[48:49]
	v_exp_f32_e32 v171, v104
	v_exp_f32_e32 v173, v105
	v_exp_f32_e32 v179, v106
	s_add_i32 m0, s5, 57344
	v_exp_f32_e32 v180, v107
	v_exp_f32_e32 v232, v108
	v_exp_f32_e32 v233, v109
	global_load_lds_dwordx4 v170, s[50:51]
	v_exp_f32_e32 v234, v110
	v_exp_f32_e32 v235, v111
	v_add_f32_e32 v190, v190, v171
	v_add_f32_e32 v191, v191, v173
	v_add_f32_e32 v190, v190, v179
	v_add_f32_e32 v191, v191, v180
	v_add_f32_e32 v190, v190, v232
	v_add_f32_e32 v191, v191, v233
	v_add_f32_e32 v190, v190, v234
	v_add_f32_e32 v191, v191, v235
	v_cvt_pk_bf16_f32 v148, v171, v173
	v_cvt_pk_bf16_f32 v149, v179, v180
	v_cvt_pk_bf16_f32 v150, v232, v233
	v_cvt_pk_bf16_f32 v151, v234, v235
	v_exp_f32_e32 v171, v112
	v_exp_f32_e32 v173, v113
	v_exp_f32_e32 v179, v114
	v_exp_f32_e32 v180, v115
	v_exp_f32_e32 v232, v116
	v_exp_f32_e32 v233, v117
	v_exp_f32_e32 v234, v118
	v_exp_f32_e32 v235, v119
	v_add_f32_e32 v190, v190, v171
	v_add_f32_e32 v191, v191, v173
	v_add_f32_e32 v190, v190, v179
	v_add_f32_e32 v191, v191, v180
	v_add_f32_e32 v190, v190, v232
	v_add_f32_e32 v191, v191, v233
	v_add_f32_e32 v190, v190, v234
	v_add_f32_e32 v191, v191, v235
	v_cvt_pk_bf16_f32 v152, v171, v173
	v_cvt_pk_bf16_f32 v153, v179, v180
	v_cvt_pk_bf16_f32 v154, v232, v233
	v_cvt_pk_bf16_f32 v155, v234, v235
	v_exp_f32_e32 v171, v120
	v_exp_f32_e32 v173, v121
	v_exp_f32_e32 v179, v122
	v_exp_f32_e32 v180, v123
	v_exp_f32_e32 v232, v124
	v_exp_f32_e32 v233, v125
	v_exp_f32_e32 v234, v126
	v_exp_f32_e32 v235, v127
	v_add_f32_e32 v190, v190, v171
	v_add_f32_e32 v191, v191, v173
	v_add_f32_e32 v190, v190, v179
	v_add_f32_e32 v191, v191, v180
	v_add_f32_e32 v190, v190, v232
	v_add_f32_e32 v191, v191, v233
	v_add_f32_e32 v190, v190, v234
	v_add_f32_e32 v191, v191, v235
	v_add_f32_e32 v190, v190, v191
	v_cmp_ngt_f32_e32 vcc, 0x71800000, v190
	v_cvt_pk_bf16_f32 v156, v171, v173
	v_cvt_pk_bf16_f32 v157, v179, v180
	v_cvt_pk_bf16_f32 v158, v232, v233
	v_cvt_pk_bf16_f32 v159, v234, v235
	s_nop 0
	s_cbranch_vccnz .Lattn_redo_L2
	v_add_f32_e32 v167, v167, v190
	s_cmp_lg_u32 s14, 0
	s_cbranch_scc1 .Lattn_tb9
	s_waitcnt vmcnt(4)
	s_barrier

.Lattn_tb10:
	ds_read_b128 v[216:219], v187 offset:0
	ds_read_b128 v[220:223], v187 offset:4096
	ds_read_b128 v[224:227], v187 offset:8192
	ds_read_b128 v[228:231], v187 offset:12288
	ds_read_b128 v[208:211], v188 offset:0
	ds_read_b128 v[212:215], v188 offset:4096
	v_exp_f32_e32 v171, v64
	v_exp_f32_e32 v173, v65
	v_exp_f32_e32 v179, v66
	s_add_i32 m0, s5, 98304
	v_exp_f32_e32 v180, v67
	v_exp_f32_e32 v232, v68
	v_exp_f32_e32 v233, v69
	global_load_lds_dwordx4 v172, s[52:53]
	v_exp_f32_e32 v234, v70
	v_exp_f32_e32 v235, v71
	v_add_f32_e32 v190, v171, v173
	s_add_i32 m0, s5, 106496
	v_add_f32_e32 v191, v179, v180
	v_add_f32_e32 v190, v190, v232
	v_add_f32_e32 v191, v191, v233
	global_load_lds_dwordx4 v172, s[54:55]
	v_add_f32_e32 v190, v190, v234
	v_add_f32_e32 v191, v191, v235
	v_cvt_pk_bf16_f32 v144, v171, v173
	s_add_i32 m0, s5, 0
	v_cvt_pk_bf16_f32 v145, v179, v180
	v_cvt_pk_bf16_f32 v146, v232, v233
	v_cvt_pk_bf16_f32 v147, v234, v235
	global_load_lds_dwordx4 v170, s[48:49]
	v_exp_f32_e32 v171, v72
	v_exp_f32_e32 v173, v73
	v_exp_f32_e32 v179, v74
	s_add_i32 m0, s5, 8192
	v_exp_f32_e32 v180, v75
	v_exp_f32_e32 v232, v76
	v_exp_f32_e32 v233, v77
	global_load_lds_dwordx4 v170, s[50:51]
	v_exp_f32_e32 v234, v78
	v_exp_f32_e32 v235, v79
	v_add_f32_e32 v190, v190, v171
	v_add_f32_e32 v191, v191, v173
	v_add_f32_e32 v190, v190, v179
	v_add_f32_e32 v191, v191, v180
	v_add_f32_e32 v190, v190, v232
	v_add_f32_e32 v191, v191, v233
	v_add_f32_e32 v190, v190, v234
	v_add_f32_e32 v191, v191, v235
	v_cvt_pk_bf16_f32 v148, v171, v173
	v_cvt_pk_bf16_f32 v149, v179, v180
	v_cvt_pk_bf16_f32 v150, v232, v233
	v_cvt_pk_bf16_f32 v151, v234, v235
	v_exp_f32_e32 v171, v80
	v_exp_f32_e32 v173, v81
	v_exp_f32_e32 v179, v82
	v_exp_f32_e32 v180, v83
	v_exp_f32_e32 v232, v84
	v_exp_f32_e32 v233, v85
	v_exp_f32_e32 v234, v86
	v_exp_f32_e32 v235, v87
	v_add_f32_e32 v190, v190, v171
	v_add_f32_e32 v191, v191, v173
	v_add_f32_e32 v190, v190, v179
	v_add_f32_e32 v191, v191, v180
	v_add_f32_e32 v190, v190, v232
	v_add_f32_e32 v191, v191, v233
	v_add_f32_e32 v190, v190, v234
	v_add_f32_e32 v191, v191, v235
	v_cvt_pk_bf16_f32 v152, v171, v173
	v_cvt_pk_bf16_f32 v153, v179, v180
	v_cvt_pk_bf16_f32 v154, v232, v233
	v_cvt_pk_bf16_f32 v155, v234, v235
	v_exp_f32_e32 v171, v88
	v_exp_f32_e32 v173, v89
	v_exp_f32_e32 v179, v90
	v_exp_f32_e32 v180, v91
	v_exp_f32_e32 v232, v92
	v_exp_f32_e32 v233, v93
	v_exp_f32_e32 v234, v94
	v_exp_f32_e32 v235, v95
	v_add_f32_e32 v190, v190, v171
	v_add_f32_e32 v191, v191, v173
	v_add_f32_e32 v190, v190, v179
	v_add_f32_e32 v191, v191, v180
	v_add_f32_e32 v190, v190, v232
	v_add_f32_e32 v191, v191, v233
	v_add_f32_e32 v190, v190, v234
	v_add_f32_e32 v191, v191, v235
	v_add_f32_e32 v190, v190, v191
	v_cmp_ngt_f32_e32 vcc, 0x71800000, v190
	v_cvt_pk_bf16_f32 v156, v171, v173
	v_cvt_pk_bf16_f32 v157, v179, v180
	v_cvt_pk_bf16_f32 v158, v232, v233
	v_cvt_pk_bf16_f32 v159, v234, v235
	s_nop 0
	s_cbranch_vccnz .Lattn_redo_L3
	v_add_f32_e32 v167, v167, v190
	s_add_i32 s42, s42, 4
	s_add_i32 s47, s47, -1
	s_cmp_lg_u32 s47, 0
	s_cbranch_scc1 .Lattn_loop_f
	s_cmp_lg_u32 s14, 0
	s_cbranch_scc1 .Lattn_tb11
	s_waitcnt vmcnt(4)
	s_barrier
